# GEMM phase prologue: both batches of stage loads issued together (one wait vmcnt(8) instead of vmcnt(2) then a second exposed latency)
# baseline (speedup 1.0000x reference)
.LBB0_225:
	s_and_b32 s47, s6, 3
	s_add_i32 m0, s22, 0x18000
	v_lshl_add_u64 v[6:7], v[6:7], 0, s[58:59]
	s_ashr_i32 s33, s92, 31
	s_lshl_b32 s56, s44, 13
	s_lshl_b32 s57, s47, 12
	global_load_lds_dwordx4 v[6:7], off
	v_lshl_add_u64 v[4:5], v[4:5], 0, s[58:59]
	s_add_i32 m0, s22, 0x1a000
	s_add_i32 s42, s22, 0x8000
	s_add_i32 s43, s22, 0xa000
	global_load_lds_dwordx4 v[4:5], off
	v_lshl_add_u64 v[0:1], v[0:1], 0, s[58:59]
	s_mov_b32 m0, s42
	s_add_u32 s6, s86, 0x40080
	global_load_lds_dwordx4 v[0:1], off
	v_lshl_add_u64 v[0:1], v[2:3], 0, s[58:59]
	s_mov_b32 m0, s43
	s_addc_u32 s7, s87, 0
	global_load_lds_dwordx4 v[0:1], off
	s_add_i32 m0, s22, 0x1c000
	v_lshl_add_u64 v[0:1], s[6:7], 0, v[98:99]
	global_load_lds_dwordx4 v[0:1], off
	v_lshl_add_u64 v[0:1], s[6:7], 0, v[134:135]
	s_add_i32 m0, s22, 0x1e000
	s_cmpk_lt_u32 s0, 0x100
	global_load_lds_dwordx4 v[0:1], off
	s_waitcnt vmcnt(8)
	s_barrier
	v_bfe_u32 v1, v8, 4, 2
	s_cselect_b64 s[72:73], -1, 0
	s_and_b32 s0, s0, 0xffffff00
	s_lshl_b32 s6, s47, 6
	v_and_b32_e32 v0, 15, v8
	v_lshlrev_b32_e32 v2, 3, v1
	v_lshlrev_b32_e32 v1, 4, v1
	s_or_b32 s0, s6, s0
	v_lshl_or_b32 v144, s44, 6, v0
	v_lshl_or_b32 v3, v0, 6, v1
	v_lshlrev_b32_e32 v4, 2, v0
	v_or3_b32 v147, s0, v1, v0
	v_lshlrev_b32_e32 v0, 14, v9
	v_and_b32_e32 v0, 0xffff8000, v0
	v_lshl_add_u32 v0, v10, 11, v0
	v_and_b32_e32 v1, 1, v9
	v_lshl_or_b32 v0, v1, 6, v0
	s_movk_i32 s0, 0x100
	v_lshl_add_u32 v136, v11, 1, v0
	v_lshlrev_b32_e32 v0, 14, v12
	v_and_b32_e32 v5, 32, v4
	v_lshl_or_b32 v146, s47, 5, v2
	v_cmp_gt_i32_e64 s[6:7], s0, v147
	v_readlane_b32 s47, v254, 42
	s_lshl_b32 s0, s44, 8
	v_and_b32_e32 v0, 0xffff8000, v0
	v_bitop3_b32 v6, v3, s56, v5 bitop3:0xde
	v_bitop3_b32 v145, v3, s57, v5 bitop3:0xde
	s_waitcnt vmcnt(6)
	s_add_i32 s44, s47, s0
	s_add_i32 s0, s0, 0
	v_lshl_add_u32 v0, v13, 11, v0
	v_and_b32_e32 v1, 1, v12
	v_readlane_b32 s56, v254, 51
	s_add_i32 s0, s0, 0x20600
	v_lshl_or_b32 v0, v1, 6, v0
	v_readlane_b32 s57, v254, 52
	v_readlane_b32 s66, v254, 47
	v_lshl_add_u32 v148, v147, 2, s47
	v_add_u32_e32 v149, s44, v4
	v_add_u32_e32 v150, s0, v4
	v_mov_b32_e32 v137, v99
	v_lshl_add_u32 v138, v14, 1, v0
	v_mov_b32_e32 v139, v99
	s_mov_b32 s44, 0
	s_mov_b32 s47, -1
	v_add_u32_e32 v151, 0, v6
	s_mov_b32 s57, s66
	s_barrier
	v_readlane_b32 s67, v254, 48
	s_branch .LBB0_228

.LBB0_295:
	s_add_i32 m0, s23, 0x18000
	v_lshl_add_u64 v[0:1], v[0:1], 0, s[58:59]
	global_load_lds_dwordx4 v[0:1], off
	v_lshl_add_u64 v[0:1], v[2:3], 0, s[58:59]
	s_add_i32 m0, s23, 0x1a000
	s_add_i32 s47, s23, 0x8000
	global_load_lds_dwordx4 v[0:1], off
	v_lshl_add_u64 v[0:1], v[8:9], 0, s[58:59]
	s_mov_b32 m0, s47
	s_add_i32 s56, s23, 0xa000
	global_load_lds_dwordx4 v[0:1], off
	v_lshl_add_u64 v[0:1], v[10:11], 0, s[58:59]
	s_mov_b32 m0, s56
	s_and_b32 s57, s9, 3
	global_load_lds_dwordx4 v[0:1], off
	s_add_i32 m0, s23, 0x1c000
	v_lshl_add_u64 v[0:1], v[4:5], 0, s[58:59]
	global_load_lds_dwordx4 v[0:1], off
	v_lshl_add_u64 v[0:1], v[6:7], 0, s[58:59]
	s_add_i32 m0, s23, 0x1e000
	s_lshl_b32 s6, s26, 13
	global_load_lds_dwordx4 v[0:1], off
	s_waitcnt vmcnt(8)
	s_barrier
	v_bfe_u32 v0, v12, 4, 2
	v_and_b32_e32 v1, 15, v12
	v_lshlrev_b32_e32 v3, 4, v0
	v_lshl_or_b32 v160, s26, 6, v1
	v_lshl_or_b32 v1, v1, 6, v3
	v_lshlrev_b32_e32 v3, 2, v12
	v_and_b32_e32 v3, 32, v3
	v_bitop3_b32 v4, v1, s6, v3 bitop3:0xde
	s_lshl_b32 s6, s57, 12
	v_lshlrev_b32_e32 v2, 3, v0
	v_bitop3_b32 v161, v1, s6, v3 bitop3:0xde
	v_cmp_eq_u32_e64 s[6:7], 0, v0
	v_add_u32_e32 v0, v15, v13
	s_lshr_b32 s67, s8, 6
	v_add_lshl_u32 v0, v0, v14, 1
	v_mov_b32_e32 v1, v99
	s_waitcnt vmcnt(6)
	s_add_i32 s88, s67, -2
	v_lshl_add_u64 v[144:145], s[72:73], 0, v[0:1]
	v_add_u32_e32 v0, v18, v16
	s_cmpk_lt_u32 s0, 0x100
	v_add_lshl_u32 v0, v0, v17, 1
	s_mov_b32 s71, s70
	s_mov_b32 s76, s70
	s_mov_b32 s77, s70
	v_lshl_or_b32 v162, s57, 5, v2
	s_cselect_b64 s[78:79], -1, 0
	s_mov_b32 s0, 0
	s_add_i32 s89, s2, -2
	v_lshl_add_u64 v[146:147], s[72:73], 0, v[0:1]
	v_add_u32_e32 v163, 0, v4
	s_barrier
	s_branch .LBB0_298

.LBB0_339:
	s_and_b32 s1, s1, 3
	s_add_i32 m0, s11, 0x18000
	v_lshl_add_u64 v[6:7], v[6:7], 0, s[58:59]
	s_ashr_i32 s26, s92, 31
	s_lshl_b32 s42, s27, 13
	s_lshl_b32 s44, s1, 12
	global_load_lds_dwordx4 v[6:7], off
	v_lshl_add_u64 v[4:5], v[4:5], 0, s[58:59]
	s_add_i32 m0, s11, 0x1a000
	s_add_i32 s33, s11, 0x8000
	s_add_i32 s43, s11, 0xa000
	global_load_lds_dwordx4 v[4:5], off
	v_lshl_add_u64 v[0:1], v[0:1], 0, s[58:59]
	s_mov_b32 m0, s33
	s_add_u32 s6, s80, 0x40080
	global_load_lds_dwordx4 v[0:1], off
	v_lshl_add_u64 v[0:1], v[2:3], 0, s[58:59]
	s_mov_b32 m0, s43
	s_addc_u32 s7, s81, 0
	global_load_lds_dwordx4 v[0:1], off
	s_add_i32 m0, s11, 0x1c000
	v_lshl_add_u64 v[0:1], s[6:7], 0, v[98:99]
	global_load_lds_dwordx4 v[0:1], off
	v_lshl_add_u64 v[0:1], s[6:7], 0, v[134:135]
	s_add_i32 m0, s11, 0x1e000
	s_cmpk_lt_u32 s0, 0x100
	global_load_lds_dwordx4 v[0:1], off
	s_waitcnt vmcnt(8)
	s_barrier
	v_bfe_u32 v1, v8, 4, 2
	v_lshlrev_b32_e32 v2, 3, v1
	v_lshl_or_b32 v146, s1, 5, v2
	s_cselect_b64 s[66:67], -1, 0
	s_and_b32 s0, s0, 0xffffff00
	s_lshl_b32 s1, s1, 6
	v_and_b32_e32 v0, 15, v8
	v_lshlrev_b32_e32 v1, 4, v1
	s_or_b32 s0, s1, s0
	v_lshl_or_b32 v144, s27, 6, v0
	v_lshl_or_b32 v3, v0, 6, v1
	v_lshlrev_b32_e32 v4, 2, v0
	v_or3_b32 v147, s0, v1, v0
	v_lshlrev_b32_e32 v0, 14, v9
	v_and_b32_e32 v0, 0xffff8000, v0
	s_movk_i32 s0, 0x100
	v_lshl_add_u32 v0, v10, 11, v0
	v_and_b32_e32 v1, 1, v9
	v_cmp_gt_i32_e64 s[6:7], s0, v147
	v_readlane_b32 s1, v254, 42
	s_lshl_b32 s0, s27, 8
	v_lshl_or_b32 v0, v1, 6, v0
	v_lshl_add_u32 v148, v147, 2, s1
	s_add_i32 s1, s1, s0
	s_add_i32 s0, s0, 0
	v_lshl_add_u32 v136, v11, 1, v0
	v_lshlrev_b32_e32 v0, 14, v12
	s_add_i32 s0, s0, 0x20600
	v_and_b32_e32 v0, 0xffff8000, v0
	v_and_b32_e32 v5, 32, v4
	s_waitcnt vmcnt(6)
	v_add_u32_e32 v149, s1, v4
	v_add_u32_e32 v150, s0, v4
	v_lshl_add_u32 v0, v13, 11, v0
	v_and_b32_e32 v1, 1, v12
	v_readlane_b32 s0, v254, 12
	v_bitop3_b32 v6, v3, s42, v5 bitop3:0xde
	v_lshl_or_b32 v0, v1, 6, v0
	v_readlane_b32 s1, v254, 13
	v_readlane_b32 s56, v254, 8
	v_bitop3_b32 v145, v3, s44, v5 bitop3:0xde
	v_mov_b32_e32 v137, v99
	v_lshl_add_u32 v138, v14, 1, v0
	v_mov_b32_e32 v139, v99
	s_mov_b32 s44, 0
	s_mov_b32 s47, -1
	v_add_u32_e32 v151, 0, v6
	s_mov_b32 s1, s56
	s_barrier
	v_readlane_b32 s57, v254, 9
	s_branch .LBB0_342
